# third division pass with chain slots removed where no wait state is needed
# baseline (speedup 1.0000x reference)
.LBB0_310:
	s_or_b64 exec, exec, s[40:41]
	v_and_b32_e32 v67, 64, v210
	v_xor_b32_e32 v66, 32, v210
	v_add_u32_e32 v67, 64, v67
	v_cmp_lt_i32_e32 vcc, v66, v67
	s_nop 1
	v_cndmask_b32_e32 v66, v210, v66, vcc
	v_lshlrev_b32_e32 v66, 2, v66
	ds_bpermute_b32 v66, v66, v233
	v_cmp_lt_u32_e32 vcc, v226, v175
	s_and_saveexec_b64 s[4:5], vcc
	s_cbranch_execz .LBB0_312
	v_readlane_b32 s6, v254, 20
	v_lshlrev_b64 v[68:69], 11, v[0:1]
	v_readlane_b32 s7, v254, 21
	s_waitcnt lgkmcnt(0)
	v_add_f32_e32 v70, v233, v66
	v_lshlrev_b32_e32 v0, 11, v226
	v_lshl_add_u64 v[68:69], s[6:7], 0, v[68:69]
	v_lshl_add_u64 v[68:69], v[68:69], 0, v[0:1]
	v_lshl_add_u64 v[66:67], v[176:177], 1, v[68:69]
	v_lshlrev_b32_e32 v0, 1, v179
	v_lshl_add_u64 v[66:67], v[66:67], 0, v[0:1]
	v_rcp_f32_e32 v0, v70
	s_nop 0
	v_pk_mul_f32 v[34:35], v[34:35], v[0:1] op_sel_hi:[1,0]
	v_pk_mul_f32 v[36:37], v[36:37], v[0:1] op_sel_hi:[1,0]
	v_cvt_pk_bf16_f32 v34, v34, v35
	v_cvt_pk_bf16_f32 v35, v36, v37
	global_store_dwordx2 v[66:67], v[34:35], off
	v_pk_mul_f32 v[34:35], v[38:39], v[0:1] op_sel_hi:[1,0]
	v_pk_mul_f32 v[36:37], v[40:41], v[0:1] op_sel_hi:[1,0]
	v_cvt_pk_bf16_f32 v34, v34, v35
	v_cvt_pk_bf16_f32 v35, v36, v37
	global_store_dwordx2 v[66:67], v[34:35], off offset:16
	v_pk_mul_f32 v[34:35], v[42:43], v[0:1] op_sel_hi:[1,0]
	v_pk_mul_f32 v[36:37], v[44:45], v[0:1] op_sel_hi:[1,0]
	v_cvt_pk_bf16_f32 v34, v34, v35
	v_cvt_pk_bf16_f32 v35, v36, v37
	global_store_dwordx2 v[66:67], v[34:35], off offset:32
	v_pk_mul_f32 v[34:35], v[46:47], v[0:1] op_sel_hi:[1,0]
	v_pk_mul_f32 v[36:37], v[48:49], v[0:1] op_sel_hi:[1,0]
	v_cvt_pk_bf16_f32 v34, v34, v35
	v_cvt_pk_bf16_f32 v35, v36, v37
	global_store_dwordx2 v[66:67], v[34:35], off offset:48
	v_pk_mul_f32 v[34:35], v[50:51], v[0:1] op_sel_hi:[1,0]
	v_pk_mul_f32 v[36:37], v[52:53], v[0:1] op_sel_hi:[1,0]
	v_pk_mul_f32 v[18:19], v[18:19], v[0:1] op_sel_hi:[1,0]
	v_pk_mul_f32 v[20:21], v[20:21], v[0:1] op_sel_hi:[1,0]
	v_pk_mul_f32 v[2:3], v[2:3], v[0:1] op_sel_hi:[1,0]
	v_pk_mul_f32 v[4:5], v[4:5], v[0:1] op_sel_hi:[1,0]
	v_cvt_pk_bf16_f32 v34, v34, v35
	v_cvt_pk_bf16_f32 v35, v36, v37
	v_cvt_pk_bf16_f32 v18, v18, v19
	v_cvt_pk_bf16_f32 v19, v20, v21
	v_cvt_pk_bf16_f32 v2, v2, v3
	v_cvt_pk_bf16_f32 v3, v4, v5
	global_store_dwordx2 v[66:67], v[34:35], off offset:64
	v_pk_mul_f32 v[34:35], v[54:55], v[0:1] op_sel_hi:[1,0]
	v_pk_mul_f32 v[36:37], v[56:57], v[0:1] op_sel_hi:[1,0]
	global_store_dwordx2 v[66:67], v[18:19], off offset:128
	v_pk_mul_f32 v[18:19], v[22:23], v[0:1] op_sel_hi:[1,0]
	v_pk_mul_f32 v[20:21], v[24:25], v[0:1] op_sel_hi:[1,0]
	global_store_dwordx2 v[66:67], v[2:3], off offset:192
	v_pk_mul_f32 v[2:3], v[6:7], v[0:1] op_sel_hi:[1,0]
	v_pk_mul_f32 v[4:5], v[8:9], v[0:1] op_sel_hi:[1,0]
	v_cvt_pk_bf16_f32 v34, v34, v35
	v_cvt_pk_bf16_f32 v35, v36, v37
	v_cvt_pk_bf16_f32 v18, v18, v19
	v_cvt_pk_bf16_f32 v19, v20, v21
	v_cvt_pk_bf16_f32 v2, v2, v3
	v_cvt_pk_bf16_f32 v3, v4, v5
	global_store_dwordx2 v[66:67], v[34:35], off offset:80
	v_pk_mul_f32 v[34:35], v[58:59], v[0:1] op_sel_hi:[1,0]
	v_pk_mul_f32 v[36:37], v[60:61], v[0:1] op_sel_hi:[1,0]
	global_store_dwordx2 v[66:67], v[18:19], off offset:144
	v_pk_mul_f32 v[18:19], v[26:27], v[0:1] op_sel_hi:[1,0]
	v_pk_mul_f32 v[20:21], v[28:29], v[0:1] op_sel_hi:[1,0]
	global_store_dwordx2 v[66:67], v[2:3], off offset:208
	v_pk_mul_f32 v[2:3], v[10:11], v[0:1] op_sel_hi:[1,0]
	v_pk_mul_f32 v[4:5], v[12:13], v[0:1] op_sel_hi:[1,0]
	v_cvt_pk_bf16_f32 v34, v34, v35
	v_cvt_pk_bf16_f32 v35, v36, v37
	v_cvt_pk_bf16_f32 v18, v18, v19
	v_cvt_pk_bf16_f32 v19, v20, v21
	v_cvt_pk_bf16_f32 v2, v2, v3
	v_cvt_pk_bf16_f32 v3, v4, v5
	global_store_dwordx2 v[66:67], v[34:35], off offset:96
	v_pk_mul_f32 v[34:35], v[62:63], v[0:1] op_sel_hi:[1,0]
	v_pk_mul_f32 v[36:37], v[64:65], v[0:1] op_sel_hi:[1,0]
	global_store_dwordx2 v[66:67], v[18:19], off offset:160
	v_pk_mul_f32 v[18:19], v[30:31], v[0:1] op_sel_hi:[1,0]
	v_pk_mul_f32 v[20:21], v[32:33], v[0:1] op_sel_hi:[1,0]
	global_store_dwordx2 v[66:67], v[2:3], off offset:224
	v_pk_mul_f32 v[2:3], v[14:15], v[0:1] op_sel_hi:[1,0]
	v_pk_mul_f32 v[4:5], v[16:17], v[0:1] op_sel_hi:[1,0]
	v_cvt_pk_bf16_f32 v34, v34, v35
	v_cvt_pk_bf16_f32 v35, v36, v37
	v_cvt_pk_bf16_f32 v18, v18, v19
	v_cvt_pk_bf16_f32 v19, v20, v21
	v_cvt_pk_bf16_f32 v2, v2, v3
	v_cvt_pk_bf16_f32 v3, v4, v5
	global_store_dwordx2 v[66:67], v[34:35], off offset:112
	global_store_dwordx2 v[66:67], v[18:19], off offset:176
	global_store_dwordx2 v[66:67], v[2:3], off offset:240

.LBB0_374:
	s_or_b64 exec, exec, s[26:27]
	s_waitcnt vmcnt(1) lgkmcnt(0)
	v_add_f32_e32 v76, v8, v76
	v_mul_f32_e32 v76, 0xbfb8aa3b, v76
	v_exp_f32_e32 v76, v76
	v_add_f32_e32 v77, v9, v77
	v_mul_f32_e32 v77, 0xbfb8aa3b, v77
	v_exp_f32_e32 v77, v77
	v_add_f32_e32 v76, 1.0, v76
	v_add_f32_e32 v77, 1.0, v77
	v_rcp_f32_e32 v76, v76
	s_nop 0
	v_add_f32_e32 v75, v7, v75
	v_mul_f32_e32 v75, 0xbfb8aa3b, v75
	v_mul_f32_e32 v76, v76, v97
	v_exp_f32_e32 v75, v75
	s_waitcnt vmcnt(0)
	v_lshlrev_b32_e32 v105, 16, v83
	v_mul_f32_e32 v76, v76, v105
	v_add_f32_e32 v75, 1.0, v75
	v_rcp_f32_e32 v77, v77
	s_nop 0
	v_mul_f32_e32 v97, 0x3fb8aa3b, v99
	v_exp_f32_e32 v109, v97
	v_add_f32_e32 v74, v6, v74
	v_mul_f32_e32 v74, 0xbfb8aa3b, v74
	v_exp_f32_e32 v74, v74
	v_rcp_f32_e32 v75, v75
	s_nop 0
	v_add_f32_e32 v74, 1.0, v74
	v_and_b32_e32 v97, 0xffff0000, v82
	v_mul_f32_e32 v75, v75, v96
	v_mul_f32_e32 v75, v75, v97
	v_mul_f32_e32 v80, 0x3fb8aa3b, v80
	v_exp_f32_e32 v108, v80
	v_lshlrev_b32_e32 v80, 16, v82
	v_mul_f32_e32 v79, 0x3fb8aa3b, v79
	v_mul_f32_e32 v78, 0x3fb8aa3b, v78
	v_exp_f32_e32 v107, v79
	v_exp_f32_e32 v106, v78
	v_rcp_f32_e32 v74, v74
	s_nop 0
	v_and_b32_e32 v79, 0xffff0000, v83
	v_mul_f32_e32 v77, v77, v81
	v_mul_f32_e32 v74, v74, v95
	v_mul_f32_e32 v77, v77, v79
	v_lshlrev_b64 v[78:79], 2, v[84:85]
	v_mul_f32_e32 v74, v74, v80
	v_lshl_add_u64 v[80:81], v[142:143], 0, v[78:79]
	v_lshl_add_u64 v[78:79], v[144:145], 0, v[78:79]
	global_store_dwordx4 v[80:81], v[106:109], off
	global_store_dwordx4 v[78:79], v[74:77], off

.LBB0_401:
	s_or_b64 exec, exec, s[26:27]
	s_waitcnt vmcnt(1) lgkmcnt(0)
	v_add_f32_e32 v76, v8, v76
	v_mul_f32_e32 v76, 0xbfb8aa3b, v76
	v_exp_f32_e32 v76, v76
	v_add_f32_e32 v77, v9, v77
	v_mul_f32_e32 v77, 0xbfb8aa3b, v77
	v_exp_f32_e32 v77, v77
	v_add_f32_e32 v76, 1.0, v76
	v_add_f32_e32 v77, 1.0, v77
	v_rcp_f32_e32 v76, v76
	s_nop 0
	v_add_f32_e32 v75, v7, v75
	v_mul_f32_e32 v75, 0xbfb8aa3b, v75
	v_mul_f32_e32 v76, v76, v99
	v_exp_f32_e32 v75, v75
	s_waitcnt vmcnt(0)
	v_lshlrev_b32_e32 v106, 16, v83
	v_mul_f32_e32 v76, v76, v106
	v_add_f32_e32 v75, 1.0, v75
	v_rcp_f32_e32 v77, v77
	s_nop 0
	v_mul_f32_e32 v99, 0x3fb8aa3b, v100
	v_exp_f32_e32 v109, v99
	v_add_f32_e32 v74, v6, v74
	v_mul_f32_e32 v74, 0xbfb8aa3b, v74
	v_exp_f32_e32 v74, v74
	v_rcp_f32_e32 v75, v75
	s_nop 0
	v_add_f32_e32 v74, 1.0, v74
	v_and_b32_e32 v99, 0xffff0000, v82
	v_mul_f32_e32 v75, v75, v97
	v_mul_f32_e32 v75, v75, v99
	v_mul_f32_e32 v80, 0x3fb8aa3b, v80
	v_exp_f32_e32 v108, v80
	v_lshlrev_b32_e32 v80, 16, v82
	v_mul_f32_e32 v79, 0x3fb8aa3b, v79
	v_mul_f32_e32 v78, 0x3fb8aa3b, v78
	v_exp_f32_e32 v107, v79
	v_exp_f32_e32 v106, v78
	v_rcp_f32_e32 v74, v74
	s_nop 0
	v_and_b32_e32 v79, 0xffff0000, v83
	v_mul_f32_e32 v77, v77, v81
	v_mul_f32_e32 v74, v74, v96
	v_mul_f32_e32 v77, v77, v79
	v_lshlrev_b64 v[78:79], 2, v[84:85]
	v_mul_f32_e32 v74, v74, v80
	v_lshl_add_u64 v[80:81], v[142:143], 0, v[78:79]
	v_lshl_add_u64 v[78:79], v[144:145], 0, v[78:79]
	global_store_dwordx4 v[80:81], v[106:109], off
	global_store_dwordx4 v[78:79], v[74:77], off

.LBB0_428:
	s_or_b64 exec, exec, s[26:27]
	s_waitcnt vmcnt(1) lgkmcnt(0)
	v_add_f32_e32 v12, v8, v12
	v_mul_f32_e32 v12, 0xbfb8aa3b, v12
	v_exp_f32_e32 v12, v12
	v_add_f32_e32 v13, v9, v13
	v_mul_f32_e32 v13, 0xbfb8aa3b, v13
	v_exp_f32_e32 v13, v13
	v_add_f32_e32 v12, 1.0, v12
	v_add_f32_e32 v13, 1.0, v13
	v_rcp_f32_e32 v12, v12
	s_nop 0
	v_add_f32_e32 v11, v7, v11
	v_mul_f32_e32 v12, v12, v23
	v_mul_f32_e32 v11, 0xbfb8aa3b, v11
	s_waitcnt vmcnt(0)
	v_lshlrev_b32_e32 v27, 16, v19
	v_exp_f32_e32 v11, v11
	v_mul_f32_e32 v12, v12, v27
	v_add_f32_e32 v11, 1.0, v11
	v_rcp_f32_e32 v13, v13
	s_nop 0
	v_mul_f32_e32 v23, 0x3fb8aa3b, v24
	v_exp_f32_e32 v25, v23
	v_add_f32_e32 v10, v6, v10
	v_mul_f32_e32 v10, 0xbfb8aa3b, v10
	v_exp_f32_e32 v10, v10
	v_rcp_f32_e32 v11, v11
	s_nop 0
	v_add_f32_e32 v10, 1.0, v10
	v_and_b32_e32 v23, 0xffff0000, v18
	v_mul_f32_e32 v11, v11, v22
	v_mul_f32_e32 v11, v11, v23
	v_mul_f32_e32 v16, 0x3fb8aa3b, v16
	v_exp_f32_e32 v24, v16
	v_lshlrev_b32_e32 v16, 16, v18
	v_rcp_f32_e32 v10, v10
	s_nop 0
	v_mul_f32_e32 v10, v10, v14
	v_mul_f32_e32 v14, 0x3fb8aa3b, v15
	v_mul_f32_e32 v0, 0x3fb8aa3b, v0
	v_exp_f32_e32 v23, v14
	v_exp_f32_e32 v22, v0
	v_and_b32_e32 v14, 0xffff0000, v19
	v_mul_f32_e32 v0, v13, v17
	v_mul_f32_e32 v13, v0, v14
	v_lshlrev_b64 v[14:15], 2, v[20:21]
	v_mul_f32_e32 v10, v10, v16
	v_lshl_add_u64 v[16:17], v[142:143], 0, v[14:15]
	v_lshl_add_u64 v[14:15], v[144:145], 0, v[14:15]
	global_store_dwordx4 v[16:17], v[22:25], off
	global_store_dwordx4 v[14:15], v[10:13], off

.LBB0_455:
	s_or_b64 exec, exec, s[26:27]
	s_waitcnt vmcnt(1) lgkmcnt(0)
	v_add_f32_e32 v12, v8, v12
	v_mul_f32_e32 v12, 0xbfb8aa3b, v12
	v_exp_f32_e32 v12, v12
	v_add_f32_e32 v13, v9, v13
	v_mul_f32_e32 v13, 0xbfb8aa3b, v13
	v_exp_f32_e32 v13, v13
	v_add_f32_e32 v12, 1.0, v12
	v_add_f32_e32 v13, 1.0, v13
	v_rcp_f32_e32 v12, v12
	s_nop 0
	v_add_f32_e32 v11, v7, v11
	v_mul_f32_e32 v11, 0xbfb8aa3b, v11
	v_mul_f32_e32 v12, v12, v24
	v_exp_f32_e32 v11, v11
	s_waitcnt vmcnt(0)
	v_lshlrev_b32_e32 v28, 16, v19
	v_mul_f32_e32 v12, v12, v28
	v_add_f32_e32 v11, 1.0, v11
	v_rcp_f32_e32 v13, v13
	s_nop 0
	v_mul_f32_e32 v24, 0x3fb8aa3b, v25
	v_exp_f32_e32 v25, v24
	v_add_f32_e32 v10, v6, v10
	v_mul_f32_e32 v10, 0xbfb8aa3b, v10
	v_exp_f32_e32 v10, v10
	v_rcp_f32_e32 v11, v11
	s_nop 0
	v_add_f32_e32 v10, 1.0, v10
	v_mul_f32_e32 v11, v11, v23
	v_and_b32_e32 v24, 0xffff0000, v18
	v_mul_f32_e32 v16, 0x3fb8aa3b, v16
	v_mul_f32_e32 v11, v11, v24
	v_exp_f32_e32 v24, v16
	v_lshlrev_b32_e32 v16, 16, v18
	v_rcp_f32_e32 v10, v10
	s_nop 0
	v_mul_f32_e32 v15, 0x3fb8aa3b, v15
	v_mul_f32_e32 v14, 0x3fb8aa3b, v14
	v_mul_f32_e32 v10, v10, v22
	v_exp_f32_e32 v23, v15
	v_exp_f32_e32 v22, v14
	v_and_b32_e32 v15, 0xffff0000, v19
	v_mul_f32_e32 v13, v13, v17
	v_mul_f32_e32 v13, v13, v15
	v_lshlrev_b64 v[14:15], 2, v[20:21]
	v_mul_f32_e32 v10, v10, v16
	v_lshl_add_u64 v[16:17], v[142:143], 0, v[14:15]
	v_lshl_add_u64 v[14:15], v[144:145], 0, v[14:15]
	global_store_dwordx4 v[16:17], v[22:25], off
	global_store_dwordx4 v[14:15], v[10:13], off

.LBB0_1141:
	s_andn2_saveexec_b64 s[12:13], s[12:13]
	s_cbranch_execz .LBB0_1143
	v_mul_f32_e32 v2, 0xbfb8aa3b, v2
	v_exp_f32_e32 v2, v2
	s_nop 0
	v_add_f32_e32 v2, 1.0, v2
	s_nop 0
	v_mov_b32_e32 v37, v1
	v_rcp_f32_e32 v2, v2
	s_nop 0
	v_lshl_add_u64 v[36:37], s[6:7], 0, v[36:37]
	v_cvt_pk_bf16_f32 v2, v2, s0
	v_lshl_add_u64 v[36:37], v[18:19], 1, v[36:37]
	global_store_short v[36:37], v2, off
